# MLA/DSA work queue: next-item atomic issued at unit start (prefetched), consumed at unit end
# baseline (speedup 1.0000x reference)
; __device__ __forceinline__ int fetch_item(unsigned* ctr, LAS unsigned* slot_unused) {
;     ...
;     __syncthreads();
;     if (opaque_tid() == 0) *slot = atomicAdd(ctr, 1u);
;     ...
;             for (int it = bx;;) {
;                 if (it >= 704) break;
;                 const int qb = 15 - it / 44, w = it % 44;
;                 if (w < 24) { const int b = w / 6, h = w % 6;
;                     att::AttnPtrs A{QMLA + h * 192, NUQ, KMLA + h * 128, 768, KROPE, VMLA + h * 128, 768, GATE + h * 128, GATE + h * 128, nullptr, 0.f, 0.f, (const float*)TAB};
.LBB0_1168:
	s_getreg_b32 s1, hwreg(HW_REG_HW_ID, 0, 6)
	s_lshl_b32 s1, s1, 2
	s_and_b32 s1, s1, 0xfc
	s_add_i32 s1, s1, 0x20040
	v_mov_b32_e32 v217, s1
	ds_read_b32 v217, v217
	s_waitcnt lgkmcnt(0)
	v_readfirstlane_b32 s1, v217
	s_cmp_lg_u32 s1, 0
	s_cbranch_scc1 .Lpf3_skip
	v_mbcnt_lo_u32_b32 v217, -1, 0
	v_mbcnt_hi_u32_b32 v217, -1, v217
	v_cmp_eq_u32_e32 vcc, 0, v217
	s_and_saveexec_b64 s[12:13], vcc
	v_mov_b32_e32 v216, 1
	global_atomic_add v216, v1, v216, s[4:5] offset:8 sc0
	s_or_b64 exec, exec, s[12:13]

; #define LAS __attribute__((address_space(3)))
; __device__ __forceinline__ int fetch_item(unsigned* ctr, LAS unsigned* slot_unused) {
;     unsigned sa = (unsigned)LDS_MAIN; asm volatile("" : "+v"(sa));
;     LAS unsigned* slot = (LAS unsigned*)(uintptr_t)sa;
;     __syncthreads();
;     if (opaque_tid() == 0) *slot = atomicAdd(ctr, 1u);
;     __syncthreads();
;     return __builtin_amdgcn_readfirstlane((int)*slot);
; }
.LBB0_1201:
	v_mov_b32_e32 v0, 0x20000
	s_waitcnt lgkmcnt(0)
	s_barrier
	s_getreg_b32 s0, hwreg(HW_REG_HW_ID, 0, 6)
	s_lshl_b32 s0, s0, 2
	s_and_b32 s0, s0, 0xfc
	s_add_i32 s0, s0, 0x20040
	v_mov_b32_e32 v2, s0
	ds_read_b32 v2, v2
	s_waitcnt lgkmcnt(0)
	v_readfirstlane_b32 s0, v2
	v_mov_b32_e32 v2, v1
	s_nop 0
	v_mbcnt_lo_u32_b32 v2, -1, v2
	v_mbcnt_hi_u32_b32 v2, -1, v2
	v_lshl_or_b32 v2, s0, 6, v2
	v_cmp_eq_u32_e32 vcc, 0, v2
	s_and_saveexec_b64 s[0:1], vcc
	s_cbranch_execz .LBB0_1167
	s_mov_b64 s[14:15], exec
	v_mbcnt_lo_u32_b32 v2, s14, 0
	v_mbcnt_hi_u32_b32 v2, s15, v2
	v_cmp_eq_u32_e32 vcc, 0, v2
	s_and_saveexec_b64 s[12:13], vcc
	s_cbranch_execz .LBB0_1166
	s_bcnt1_i32_b64 s14, s[14:15]
	v_mov_b32_e32 v3, v216
	s_branch .LBB0_1166
